# hoist the 4 row loads ahead of the first wait in the x->bf16 row loops (phase 0, phase 3) and the second-half loads in the final rmsnorm loop; counted vmcnt
# baseline (speedup 1.0000x reference)
.LBB0_66:
	s_or_b64 exec, exec, s[16:17]
	v_lshlrev_b64 v[40:41], 11, v[20:21]
	v_lshl_add_u64 v[22:23], v[22:23], 0, v[18:19]
	v_lshl_add_u64 v[52:53], v[12:13], 0, v[40:41]
	global_load_dwordx4 v[36:39], v[22:23], off
	global_load_dwordx4 v[40:43], v[22:23], off offset:1024
	global_load_dwordx4 v[44:47], v[22:23], off offset:2048
	global_load_dwordx4 v[48:51], v[22:23], off offset:3072
	s_waitcnt vmcnt(3)
	v_cvt_pk_bf16_f32 v128, v36, v37
	v_cvt_pk_bf16_f32 v129, v38, v39
	v_mul_f32_e32 v4, v37, v37
	global_store_dwordx2 v[52:53], v[128:129], off
	v_fmac_f32_e32 v4, v36, v36
	v_fmac_f32_e32 v4, v38, v38
	v_fmac_f32_e32 v4, v39, v39
	s_waitcnt vmcnt(3)
	v_cvt_pk_bf16_f32 v130, v40, v41
	v_cvt_pk_bf16_f32 v131, v42, v43
	v_mul_f32_e32 v22, v41, v41
	global_store_dwordx2 v[52:53], v[130:131], off offset:512
	v_fmac_f32_e32 v22, v40, v40
	v_fmac_f32_e32 v22, v42, v42
	v_fmac_f32_e32 v22, v43, v43
	v_add_f32_e32 v4, v4, v22
	s_waitcnt vmcnt(3)
	v_cvt_pk_bf16_f32 v132, v44, v45
	v_cvt_pk_bf16_f32 v133, v46, v47
	v_mul_f32_e32 v22, v45, v45
	global_store_dwordx2 v[52:53], v[132:133], off offset:1024
	v_fmac_f32_e32 v22, v44, v44
	v_fmac_f32_e32 v22, v46, v46
	v_fmac_f32_e32 v22, v47, v47
	v_add_f32_e32 v4, v4, v22
	s_waitcnt vmcnt(3)
	v_mul_f32_e32 v22, v49, v49
	v_fmac_f32_e32 v22, v48, v48
	v_fmac_f32_e32 v22, v50, v50
	v_fmac_f32_e32 v22, v51, v51
	v_add_f32_e32 v4, v4, v22
	ds_bpermute_b32 v22, v9, v4
	v_cvt_pk_bf16_f32 v134, v48, v49
	v_cvt_pk_bf16_f32 v135, v50, v51
	global_store_dwordx2 v[52:53], v[134:135], off offset:1536
	s_waitcnt lgkmcnt(0)
	v_add_f32_e32 v4, v4, v22
	ds_bpermute_b32 v22, v11, v4
	s_waitcnt lgkmcnt(0)
	v_add_f32_e32 v4, v4, v22
	ds_bpermute_b32 v22, v32, v4
	s_waitcnt lgkmcnt(0)
	v_add_f32_e32 v4, v4, v22
	ds_bpermute_b32 v22, v33, v4
	s_waitcnt lgkmcnt(0)
	v_add_f32_e32 v4, v4, v22
	ds_bpermute_b32 v22, v34, v4
	s_waitcnt lgkmcnt(0)
	v_add_f32_e32 v4, v4, v22
	ds_bpermute_b32 v22, v35, v4
	s_and_saveexec_b64 s[16:17], s[0:1]
	s_cbranch_execz .LBB0_63
	v_readlane_b32 s20, v254, 52
	v_readlane_b32 s21, v254, 53
	s_waitcnt lgkmcnt(0)
	v_add_f32_e32 v4, v4, v22
	v_lshl_add_u64 v[20:21], v[20:21], 2, s[20:21]
	v_add_co_u32_e32 v22, vcc, 0x40000, v20
	global_store_dword v[20:21], v4, off
	s_nop 0
	v_addc_co_u32_e32 v23, vcc, 0, v21, vcc
	global_store_dword v[22:23], v5, off
	v_add_co_u32_e32 v22, vcc, 0x80000, v20
	s_nop 1
	v_addc_co_u32_e32 v23, vcc, 0, v21, vcc
	v_add_co_u32_e32 v20, vcc, 0xc0000, v20
	global_store_dword v[22:23], v5, off
	s_nop 0
	v_addc_co_u32_e32 v21, vcc, 0, v21, vcc
	global_store_dword v[20:21], v5, off
	s_branch .LBB0_63

.LBB0_266:
	s_or_b64 exec, exec, s[10:11]
	v_lshlrev_b64 v[10:11], 11, v[10:11]
	v_lshl_add_u64 v[16:17], v[12:13], 0, v[8:9]
	v_lshl_add_u64 v[18:19], v[2:3], 0, v[10:11]
	global_load_dwordx4 v[20:23], v[16:17], off
	global_load_dwordx4 v[24:27], v[16:17], off offset:1024
	global_load_dwordx4 v[28:31], v[16:17], off offset:2048
	global_load_dwordx4 v[32:35], v[16:17], off offset:3072
	v_lshl_add_u64 v[4:5], v[4:5], 0, s[4:5]
	v_lshl_add_u64 v[6:7], v[6:7], 0, s[6:7]
	v_cmp_lt_i32_e32 vcc, s13, v4
	s_waitcnt vmcnt(3)
	v_cvt_pk_bf16_f32 v36, v20, v21
	v_cvt_pk_bf16_f32 v37, v22, v23
	s_or_b64 s[8:9], vcc, s[8:9]
	global_store_dwordx2 v[18:19], v[36:37], off
	s_waitcnt vmcnt(3)
	v_cvt_pk_bf16_f32 v38, v24, v25
	v_cvt_pk_bf16_f32 v39, v26, v27
	global_store_dwordx2 v[18:19], v[38:39], off offset:512
	s_waitcnt vmcnt(3)
	v_cvt_pk_bf16_f32 v40, v28, v29
	v_cvt_pk_bf16_f32 v41, v30, v31
	global_store_dwordx2 v[18:19], v[40:41], off offset:1024
	s_waitcnt vmcnt(3)
	v_cvt_pk_bf16_f32 v42, v32, v33
	v_cvt_pk_bf16_f32 v43, v34, v35
	global_store_dwordx2 v[18:19], v[42:43], off offset:1536
	s_andn2_b64 exec, exec, s[8:9]
	s_cbranch_execz .LBB0_269

.LBB0_975:
	v_lshl_add_u64 v[14:15], s[14:15], 0, v[2:3]
	v_add_co_u32_e32 v18, vcc, 0x6c80000, v14
	v_lshl_add_u64 v[16:17], s[14:15], 0, v[4:5]
	s_nop 0
	v_addc_co_u32_e32 v19, vcc, 0, v15, vcc
	v_add_co_u32_e32 v20, vcc, 0x6cc0000, v14
	global_load_dwordx4 v[10:13], v[0:1], off
	s_nop 0
	v_addc_co_u32_e32 v21, vcc, 0, v15, vcc
	v_add_co_u32_e32 v22, vcc, 0x6d00000, v14
	global_load_dword v24, v[18:19], off
	global_load_dword v26, v[20:21], off
	v_addc_co_u32_e32 v23, vcc, 0, v15, vcc
	v_add_co_u32_e32 v14, vcc, 0x6d40000, v14
	v_add_u32_e32 v8, s0, v8
	s_nop 0
	v_addc_co_u32_e32 v15, vcc, 0, v15, vcc
	global_load_dword v25, v[22:23], off
	global_load_dword v27, v[14:15], off
	v_add_co_u32_e32 v28, vcc, s10, v16
	v_lshl_add_u64 v[2:3], v[2:3], 0, s[2:3]
	s_nop 0
	v_addc_co_u32_e32 v29, vcc, 0, v17, vcc
	global_load_dwordx4 v[14:17], v[28:29], off
	global_load_dwordx4 v[18:21], v[0:1], off offset:16
	global_load_dwordx4 v[30:33], v[28:29], off offset:1024
	global_load_dwordx4 v[34:37], v[0:1], off offset:2048
	global_load_dwordx4 v[38:41], v[0:1], off offset:2064
	v_lshl_add_u64 v[4:5], v[4:5], 0, s[4:5]
	s_waitcnt vmcnt(3)
	v_pk_add_f32 v[22:23], v[24:25], v[26:27]
	s_nop 0
	v_add_f32_e32 v26, v22, v23
	v_fmamk_f32 v26, v26, 0x3a800000, v9
	v_cmp_gt_f32_e32 vcc, s1, v26
	v_lshlrev_b32_e32 v22, 16, v14
	v_and_b32_e32 v23, 0xffff0000, v14
	v_lshlrev_b32_e32 v14, 16, v15
	v_and_b32_e32 v15, 0xffff0000, v15
	v_lshlrev_b32_e32 v24, 16, v16
	v_and_b32_e32 v25, 0xffff0000, v16
	v_pk_mul_f32 v[12:13], v[12:13], v[14:15]
	v_pk_mul_f32 v[14:15], v[18:19], v[24:25]
	v_mul_f32_e32 v18, 0x4b800000, v26
	v_cndmask_b32_e32 v18, v26, v18, vcc
	v_rsq_f32_e32 v18, v18
	v_lshlrev_b32_e32 v16, 16, v17
	v_and_b32_e32 v17, 0xffff0000, v17
	v_pk_mul_f32 v[10:11], v[10:11], v[22:23]
	v_mul_f32_e32 v19, 0x45800000, v18
	v_cndmask_b32_e32 v22, v18, v19, vcc
	v_pk_mul_f32 v[16:17], v[20:21], v[16:17]
	v_pk_mul_f32 v[12:13], v[22:23], v[12:13] op_sel_hi:[0,1]
	v_pk_mul_f32 v[10:11], v[22:23], v[10:11] op_sel_hi:[0,1]
	v_pk_mul_f32 v[16:17], v[22:23], v[16:17] op_sel_hi:[0,1]
	v_pk_mul_f32 v[14:15], v[22:23], v[14:15] op_sel_hi:[0,1]
	global_store_dwordx4 v[6:7], v[10:13], off offset:-2064
	global_store_dwordx4 v[6:7], v[14:17], off offset:-2048
	v_cmp_lt_i32_e32 vcc, s11, v8
	s_or_b64 s[8:9], vcc, s[8:9]
	s_waitcnt vmcnt(2)
	v_lshlrev_b32_e32 v24, 16, v30
	v_and_b32_e32 v25, 0xffff0000, v30
	v_lshlrev_b32_e32 v42, 16, v31
	v_and_b32_e32 v43, 0xffff0000, v31
	v_lshlrev_b32_e32 v26, 16, v32
	v_and_b32_e32 v27, 0xffff0000, v32
	v_lshlrev_b32_e32 v44, 16, v33
	v_and_b32_e32 v45, 0xffff0000, v33
	v_pk_mul_f32 v[34:35], v[34:35], v[24:25]
	v_pk_mul_f32 v[36:37], v[36:37], v[42:43]
	v_pk_mul_f32 v[38:39], v[38:39], v[26:27]
	v_pk_mul_f32 v[40:41], v[40:41], v[44:45]
	v_pk_mul_f32 v[46:47], v[22:23], v[34:35] op_sel_hi:[0,1]
	v_pk_mul_f32 v[48:49], v[22:23], v[36:37] op_sel_hi:[0,1]
	v_pk_mul_f32 v[50:51], v[22:23], v[38:39] op_sel_hi:[0,1]
	v_pk_mul_f32 v[52:53], v[22:23], v[40:41] op_sel_hi:[0,1]
	global_store_dwordx4 v[6:7], v[46:49], off offset:-16
	global_store_dwordx4 v[6:7], v[50:53], off
	v_lshl_add_u64 v[6:7], v[6:7], 0, s[6:7]
	s_andn2_b64 exec, exec, s[8:9]
	s_cbranch_execnz .LBB0_975
